# code placement: conv-gate K-loop head at byte phase 28 mod 64 (others 16 / 12)
# baseline (speedup 1.0000x reference)
; #define PG8_STAGE(bufoff, gbase, voff) do { _Pragma("unroll") for (int _i = 0; _i < 2; ++_i) \
;         __builtin_amdgcn_global_load_lds((const unsigned*)((const char*)(gbase) + (voff)[_i]), (LAS unsigned*)(lds + (bufoff) + ldsw + _i * 8192), 16, 0, 0); } while (0)
; #define PG8_LDA(dst, b, h) do { _Pragma("unroll") for (int m = 0; m < 4; ++m) _Pragma("unroll") for (int k = 0; k < 2; ++k) dst[m][k] = *(const LAS bf16x8*)(lds + PG8_SA(b, h) + aoff + m * 2048 + k * 1024); } while (0)
; #define PG8_LDB(dst, b, h) do { _Pragma("unroll") for (int n = 0; n < 2; ++n) _Pragma("unroll") for (int k = 0; k < 2; ++k) dst[n][k] = *(const LAS bf16x8*)(lds + PG8_SB(b, h) + boff + n * 2048 + k * 1024); } while (0)
; #define PG8_MMA(ai, bj, At, Bt) do { __builtin_amdgcn_s_setprio(1); _Pragma("unroll") for (int m = 0; m < 4; ++m) _Pragma("unroll") for (int n = 0; n < 2; ++n) _Pragma("unroll") for (int k = 0; k < 2; ++k) \
;         acc[ai][bj][m][n] = __builtin_amdgcn_mfma_f32_16x16x32_bf16(Bt[n][k], At[m][k], acc[ai][bj][m][n], 0, 0, 0); __builtin_amdgcn_s_setprio(0); } while (0)
; #define PG8_WAIT_V(n) asm volatile("s_waitcnt vmcnt(" #n ")" ::: "memory")
; #define PG8_WAIT_L(n) asm volatile("s_waitcnt lgkmcnt(" #n ")" ::: "memory")
; #define PG8_BAR __builtin_amdgcn_s_barrier()
; #define PG8_SCHED __builtin_amdgcn_sched_barrier(0)
;     ...
;         const bool has_next = S.next(ui + 1, nxt);
;         const char* nA = has_next ? nxt.A : cA; const char* nB = has_next ? nxt.B : cB;
;         for (int t = 0; t < nt; t += 2) {
;             const bool last = (t == nt - 2);
;             const char* a1 = cA + (size_t)(t + 1) * kstep;
;             const char* a2 = last ? nA : cA + (size_t)(t + 2) * kstep; const char* b2 = last ? nB : cB + (size_t)(t + 2) * kstep;
;             const char* a3 = a2 + kstep; const char* b3 = b2 + kstep;
;             PG8_LDB(B0, 0, 0); PG8_LDB(B1, 0, 1); PG8_SCHED; PG8_LDA(At, 0, 0); PG8_STAGE(PG8_SA(1, 1), a1 + hstepA, voffA);
;             PG8_WAIT_V(8); PG8_WAIT_L(0); PG8_BAR; PG8_MMA(0, 0, At, B0); PG8_MMA(0, 1, At, B1); PG8_BAR; PG8_SCHED;
;             PG8_LDA(At, 0, 1); PG8_STAGE(PG8_SB(0, 0), b2, voffB); PG8_STAGE(PG8_SB(0, 1), b2 + hstepB, voffB); PG8_STAGE(PG8_SA(0, 0), a2, voffA);
;             PG8_WAIT_V(8); PG8_WAIT_L(0); PG8_BAR; PG8_MMA(1, 0, At, B0); PG8_MMA(1, 1, At, B1); PG8_BAR; PG8_SCHED;
.LBB0_317:
	s_mov_b64 s[54:55], s[68:69]
	v_mov_b32_e32 v189, v128
	s_xor_b64 s[66:67], s[64:65], -1
	v_mov_b32_e32 v128, s55
	s_mov_b64 s[36:37], s[38:39]
	s_and_b64 s[0:1], s[64:65], exec
	v_cndmask_b32_e64 v132, v161, v128, s[64:65]
	v_mov_b32_e32 v128, s54
	s_mov_b64 s[6:7], s[56:57]
	s_mov_b64 s[14:15], s[58:59]
	s_mov_b32 s26, s19
	s_cselect_b32 s13, s37, s3
	s_cselect_b32 s56, s36, s2
	v_cndmask_b32_e64 v133, v160, v128, s[64:65]
	s_mov_b32 s38, 0
	s_mov_b64 s[0:1], 0x100
	v_mov_b64_e32 v[128:129], v[172:173]
	v_mov_b64_e32 v[130:131], v[170:171]
	s_nop 0
	s_nop 0
.LBB0_318:
	s_add_i32 s57, s38, 2
	s_add_u32 s19, s2, s0
	s_addc_u32 s27, s3, s1
	s_add_i32 s58, 0, 0x10000
	s_cmp_eq_u32 s51, s38
	s_cselect_b32 s39, s13, s27
	s_cselect_b32 s38, s56, s19
	s_cselect_b64 vcc, -1, 0
	s_add_i32 s19, 0, 0x14000
	v_lshl_add_u64 v[150:151], v[160:161], 0, s[0:1]
	v_add_u32_e32 v146, s58, v181
	s_waitcnt lgkmcnt(0)
	v_add_u32_e32 v178, s19, v181
	ds_read_b128 v[134:137], v146
	ds_read_b128 v[138:141], v146 offset:1024
	ds_read_b128 v[142:145], v146 offset:2048
	ds_read_b128 v[146:149], v146 offset:3072
	v_cndmask_b32_e32 v159, v151, v132, vcc
	v_cndmask_b32_e32 v158, v150, v133, vcc
	ds_read_b128 v[150:153], v178
	ds_read_b128 v[154:157], v178 offset:1024
	ds_read_b128 v[174:177], v178 offset:2048
	ds_read_b128 v[190:193], v178 offset:3072
	v_lshl_add_u64 v[178:179], s[2:3], 0, v[130:131]
	s_add_i32 m0, s11, 0xc000
	ds_read_b128 v[194:197], v188
	ds_read_b128 v[198:201], v188 offset:1024
	ds_read_b128 v[202:205], v188 offset:2048
	ds_read_b128 v[224:227], v188 offset:3072
	ds_read_b128 v[228:231], v188 offset:4096
	ds_read_b128 v[232:235], v188 offset:5120
	ds_read_b128 v[236:239], v188 offset:6144
	ds_read_b128 v[240:243], v188 offset:7168
	global_load_lds_dwordx4 v[178:179], off
	v_lshl_add_u64 v[178:179], s[2:3], 0, v[128:129]
	s_add_i32 m0, s11, 0xe000
	s_nop 0
	global_load_lds_dwordx4 v[178:179], off
	s_waitcnt vmcnt(8)
	s_waitcnt lgkmcnt(0)
	s_barrier
	s_setprio 1
	s_waitcnt lgkmcnt(0)
	v_mfma_f32_16x16x32_bf16 v[124:127], v[134:137], v[194:197], v[124:127]
	v_mfma_f32_16x16x32_bf16 v[120:123], v[142:145], v[194:197], v[120:123]
	v_mfma_f32_16x16x32_bf16 v[116:119], v[134:137], v[202:205], v[116:119]
	v_mfma_f32_16x16x32_bf16 v[112:115], v[142:145], v[202:205], v[112:115]
	v_mfma_f32_16x16x32_bf16 v[108:111], v[134:137], v[228:231], v[108:111]
	v_mfma_f32_16x16x32_bf16 v[104:107], v[142:145], v[228:231], v[104:107]
	v_mfma_f32_16x16x32_bf16 v[100:103], v[134:137], v[236:239], v[100:103]
	v_mfma_f32_16x16x32_bf16 v[96:99], v[142:145], v[236:239], v[96:99]
	v_mfma_f32_16x16x32_bf16 v[124:127], v[138:141], v[198:201], v[124:127]
	v_mfma_f32_16x16x32_bf16 v[120:123], v[146:149], v[198:201], v[120:123]
	v_mfma_f32_16x16x32_bf16 v[116:119], v[138:141], v[224:227], v[116:119]
	v_mfma_f32_16x16x32_bf16 v[112:115], v[146:149], v[224:227], v[112:115]
	v_mfma_f32_16x16x32_bf16 v[108:111], v[138:141], v[232:235], v[108:111]
	v_mfma_f32_16x16x32_bf16 v[104:107], v[146:149], v[232:235], v[104:107]
	v_mfma_f32_16x16x32_bf16 v[100:103], v[138:141], v[240:243], v[100:103]
	v_mfma_f32_16x16x32_bf16 v[96:99], v[146:149], v[240:243], v[96:99]
	s_setprio 0
	s_setprio 1
	v_mfma_f32_16x16x32_bf16 v[92:95], v[150:153], v[194:197], v[92:95]
	v_mfma_f32_16x16x32_bf16 v[88:91], v[174:177], v[194:197], v[88:91]
	v_mfma_f32_16x16x32_bf16 v[84:87], v[150:153], v[202:205], v[84:87]
	v_mfma_f32_16x16x32_bf16 v[80:83], v[174:177], v[202:205], v[80:83]
	v_mfma_f32_16x16x32_bf16 v[76:79], v[150:153], v[228:231], v[76:79]
	v_mfma_f32_16x16x32_bf16 v[72:75], v[174:177], v[228:231], v[72:75]
	v_mfma_f32_16x16x32_bf16 v[68:71], v[150:153], v[236:239], v[68:71]
	v_mfma_f32_16x16x32_bf16 v[64:67], v[174:177], v[236:239], v[64:67]
	v_mfma_f32_16x16x32_bf16 v[92:95], v[154:157], v[198:201], v[92:95]
	v_mfma_f32_16x16x32_bf16 v[88:91], v[190:193], v[198:201], v[88:91]
	v_mfma_f32_16x16x32_bf16 v[84:87], v[154:157], v[224:227], v[84:87]
	v_mfma_f32_16x16x32_bf16 v[80:83], v[190:193], v[224:227], v[80:83]
	v_mfma_f32_16x16x32_bf16 v[76:79], v[154:157], v[232:235], v[76:79]
	v_mfma_f32_16x16x32_bf16 v[72:75], v[190:193], v[232:235], v[72:75]
	v_mfma_f32_16x16x32_bf16 v[68:71], v[154:157], v[240:243], v[68:71]
	v_mfma_f32_16x16x32_bf16 v[64:67], v[190:193], v[240:243], v[64:67]
	s_setprio 0
	s_barrier
	s_add_i32 s27, s58, s10
	v_lshl_add_u64 v[178:179], v[158:159], 0, v[164:165]
	s_mov_b32 m0, s27
	ds_read_b128 v[194:197], v188 offset:16384
	ds_read_b128 v[198:201], v188 offset:17408
	ds_read_b128 v[202:205], v188 offset:18432
	ds_read_b128 v[224:227], v188 offset:19456
	ds_read_b128 v[228:231], v188 offset:20480
	ds_read_b128 v[232:235], v188 offset:21504
	ds_read_b128 v[236:239], v188 offset:22528
	ds_read_b128 v[240:243], v188 offset:23552
	global_load_lds_dwordx4 v[178:179], off
	v_lshl_add_u64 v[212:213], v[158:159], 0, v[168:169]
	s_add_i32 m0, s27, 0x2000
	v_lshl_add_u64 v[158:159], v[158:159], 0, s[96:97]
	s_add_i32 s19, s19, s10
	global_load_lds_dwordx4 v[212:213], off
	v_lshl_add_u64 v[218:219], v[158:159], 0, v[164:165]
	s_mov_b32 m0, s19
	v_lshl_add_u64 v[158:159], v[158:159], 0, v[168:169]
	global_load_lds_dwordx4 v[218:219], off
	s_add_i32 m0, s19, 0x2000
	v_lshl_add_u64 v[244:245], s[38:39], 0, v[162:163]
	global_load_lds_dwordx4 v[158:159], off
	s_mov_b32 m0, s11
	v_lshl_add_u64 v[246:247], s[38:39], 0, v[166:167]
	global_load_lds_dwordx4 v[244:245], off
	s_mov_b32 m0, s20
	s_nop 0
	global_load_lds_dwordx4 v[246:247], off
	s_waitcnt vmcnt(8)
	s_waitcnt lgkmcnt(0)
	s_barrier
; #define PG8_STAGE(bufoff, gbase, voff) do { _Pragma("unroll") for (int _i = 0; _i < 2; ++_i) \
;         __builtin_amdgcn_global_load_lds((const unsigned*)((const char*)(gbase) + (voff)[_i]), (LAS unsigned*)(lds + (bufoff) + ldsw + _i * 8192), 16, 0, 0); } while (0)
; #define PG8_LDA(dst, b, h) do { _Pragma("unroll") for (int m = 0; m < 4; ++m) _Pragma("unroll") for (int k = 0; k < 2; ++k) dst[m][k] = *(const LAS bf16x8*)(lds + PG8_SA(b, h) + aoff + m * 2048 + k * 1024); } while (0)
; #define PG8_LDB(dst, b, h) do { _Pragma("unroll") for (int n = 0; n < 2; ++n) _Pragma("unroll") for (int k = 0; k < 2; ++k) dst[n][k] = *(const LAS bf16x8*)(lds + PG8_SB(b, h) + boff + n * 2048 + k * 1024); } while (0)
; #define PG8_MMA(ai, bj, At, Bt) do { __builtin_amdgcn_s_setprio(1); _Pragma("unroll") for (int m = 0; m < 4; ++m) _Pragma("unroll") for (int n = 0; n < 2; ++n) _Pragma("unroll") for (int k = 0; k < 2; ++k) \
;         acc[ai][bj][m][n] = __builtin_amdgcn_mfma_f32_16x16x32_bf16(Bt[n][k], At[m][k], acc[ai][bj][m][n], 0, 0, 0); __builtin_amdgcn_s_setprio(0); } while (0)
; #define PG8_WAIT_V(n) asm volatile("s_waitcnt vmcnt(" #n ")" ::: "memory")
; #define PG8_WAIT_L(n) asm volatile("s_waitcnt lgkmcnt(" #n ")" ::: "memory")
; #define PG8_BAR __builtin_amdgcn_s_barrier()
; #define PG8_SCHED __builtin_amdgcn_sched_barrier(0)
;     ...
;             PG8_WAIT_V(8); PG8_WAIT_L(0); PG8_BAR; PG8_MMA(1, 0, At, B0); PG8_MMA(1, 1, At, B1); PG8_BAR; PG8_SCHED;
;             PG8_LDB(B0, 1, 0); PG8_LDB(B1, 1, 1); PG8_SCHED; PG8_LDA(At, 1, 0); PG8_STAGE(PG8_SA(0, 1), a2 + hstepA, voffA);
;             PG8_WAIT_V(8); PG8_WAIT_L(0); PG8_BAR; PG8_MMA(0, 0, At, B0); PG8_MMA(0, 1, At, B1); PG8_BAR; PG8_SCHED;
	s_setprio 1
	s_waitcnt lgkmcnt(0)
	v_mfma_f32_16x16x32_bf16 v[60:63], v[134:137], v[194:197], v[60:63]
	v_mfma_f32_16x16x32_bf16 v[56:59], v[142:145], v[194:197], v[56:59]
	v_mfma_f32_16x16x32_bf16 v[52:55], v[134:137], v[202:205], v[52:55]
	v_mfma_f32_16x16x32_bf16 v[48:51], v[142:145], v[202:205], v[48:51]
	v_mfma_f32_16x16x32_bf16 v[44:47], v[134:137], v[228:231], v[44:47]
	v_mfma_f32_16x16x32_bf16 v[40:43], v[142:145], v[228:231], v[40:43]
	v_mfma_f32_16x16x32_bf16 v[36:39], v[134:137], v[236:239], v[36:39]
	v_mfma_f32_16x16x32_bf16 v[32:35], v[142:145], v[236:239], v[32:35]
	v_mfma_f32_16x16x32_bf16 v[60:63], v[138:141], v[198:201], v[60:63]
	v_mfma_f32_16x16x32_bf16 v[56:59], v[146:149], v[198:201], v[56:59]
	v_mfma_f32_16x16x32_bf16 v[52:55], v[138:141], v[224:227], v[52:55]
	v_mfma_f32_16x16x32_bf16 v[48:51], v[146:149], v[224:227], v[48:51]
	v_mfma_f32_16x16x32_bf16 v[44:47], v[138:141], v[232:235], v[44:47]
	v_mfma_f32_16x16x32_bf16 v[40:43], v[146:149], v[232:235], v[40:43]
	v_mfma_f32_16x16x32_bf16 v[36:39], v[138:141], v[240:243], v[36:39]
	v_mfma_f32_16x16x32_bf16 v[32:35], v[146:149], v[240:243], v[32:35]
	s_setprio 0
	s_setprio 1
	v_mfma_f32_16x16x32_bf16 v[28:31], v[150:153], v[194:197], v[28:31]
	v_mfma_f32_16x16x32_bf16 v[24:27], v[174:177], v[194:197], v[24:27]
	v_mfma_f32_16x16x32_bf16 v[20:23], v[150:153], v[202:205], v[20:23]
	v_mfma_f32_16x16x32_bf16 v[16:19], v[174:177], v[202:205], v[16:19]
	v_mfma_f32_16x16x32_bf16 v[12:15], v[150:153], v[228:231], v[12:15]
	v_mfma_f32_16x16x32_bf16 v[8:11], v[174:177], v[228:231], v[8:11]
	v_mfma_f32_16x16x32_bf16 v[4:7], v[150:153], v[236:239], v[4:7]
	v_mfma_f32_16x16x32_bf16 v[0:3], v[174:177], v[236:239], v[0:3]
	v_mfma_f32_16x16x32_bf16 v[28:31], v[154:157], v[198:201], v[28:31]
	v_mfma_f32_16x16x32_bf16 v[24:27], v[190:193], v[198:201], v[24:27]
	v_mfma_f32_16x16x32_bf16 v[20:23], v[154:157], v[224:227], v[20:23]
	v_mfma_f32_16x16x32_bf16 v[16:19], v[190:193], v[224:227], v[16:19]
	v_mfma_f32_16x16x32_bf16 v[12:15], v[154:157], v[232:235], v[12:15]
	v_mfma_f32_16x16x32_bf16 v[8:11], v[190:193], v[232:235], v[8:11]
	v_mfma_f32_16x16x32_bf16 v[4:7], v[154:157], v[240:243], v[4:7]
	v_mfma_f32_16x16x32_bf16 v[0:3], v[190:193], v[240:243], v[0:3]
	s_setprio 0
	s_barrier
	s_add_i32 s19, 0, 0x18000
	s_add_i32 s27, 0, 0x1c000
	v_add_u32_e32 v146, s19, v181
	v_add_u32_e32 v182, s27, v181
	ds_read_b128 v[134:137], v146
	ds_read_b128 v[138:141], v146 offset:1024
	ds_read_b128 v[142:145], v146 offset:2048
	ds_read_b128 v[146:149], v146 offset:3072
	ds_read_b128 v[150:153], v182
	ds_read_b128 v[154:157], v182 offset:1024
	ds_read_b128 v[174:177], v182 offset:2048
	ds_read_b128 v[190:193], v182 offset:3072
	s_add_u32 s38, s38, s96
	s_addc_u32 s39, s39, 0
	s_mov_b32 m0, s48
	v_lshl_add_u64 v[248:249], s[38:39], 0, v[162:163]
	ds_read_b128 v[194:197], v188 offset:32768
	ds_read_b128 v[198:201], v188 offset:33792
	ds_read_b128 v[202:205], v188 offset:34816
	ds_read_b128 v[224:227], v188 offset:35840
	ds_read_b128 v[228:231], v188 offset:36864
	ds_read_b128 v[232:235], v188 offset:37888
	ds_read_b128 v[236:239], v188 offset:38912
	ds_read_b128 v[240:243], v188 offset:39936
	global_load_lds_dwordx4 v[248:249], off
	v_lshl_add_u64 v[248:249], s[38:39], 0, v[166:167]
	s_mov_b32 m0, s49
	s_nop 0
	global_load_lds_dwordx4 v[248:249], off
	s_waitcnt vmcnt(8)
	s_waitcnt lgkmcnt(0)
	s_barrier
	s_setprio 1
	s_waitcnt lgkmcnt(0)
	v_mfma_f32_16x16x32_bf16 v[124:127], v[134:137], v[194:197], v[124:127]
	v_mfma_f32_16x16x32_bf16 v[120:123], v[142:145], v[194:197], v[120:123]
	v_mfma_f32_16x16x32_bf16 v[116:119], v[134:137], v[202:205], v[116:119]
	v_mfma_f32_16x16x32_bf16 v[112:115], v[142:145], v[202:205], v[112:115]
	v_mfma_f32_16x16x32_bf16 v[108:111], v[134:137], v[228:231], v[108:111]
	v_mfma_f32_16x16x32_bf16 v[104:107], v[142:145], v[228:231], v[104:107]
	v_mfma_f32_16x16x32_bf16 v[100:103], v[134:137], v[236:239], v[100:103]
	v_mfma_f32_16x16x32_bf16 v[96:99], v[142:145], v[236:239], v[96:99]
	v_mfma_f32_16x16x32_bf16 v[124:127], v[138:141], v[198:201], v[124:127]
	v_mfma_f32_16x16x32_bf16 v[120:123], v[146:149], v[198:201], v[120:123]
	v_mfma_f32_16x16x32_bf16 v[116:119], v[138:141], v[224:227], v[116:119]
	v_mfma_f32_16x16x32_bf16 v[112:115], v[146:149], v[224:227], v[112:115]
	v_mfma_f32_16x16x32_bf16 v[108:111], v[138:141], v[232:235], v[108:111]
	v_mfma_f32_16x16x32_bf16 v[104:107], v[146:149], v[232:235], v[104:107]
	v_mfma_f32_16x16x32_bf16 v[100:103], v[138:141], v[240:243], v[100:103]
	v_mfma_f32_16x16x32_bf16 v[96:99], v[146:149], v[240:243], v[96:99]
	s_setprio 0
	s_setprio 1
	v_mfma_f32_16x16x32_bf16 v[92:95], v[150:153], v[194:197], v[92:95]
	v_mfma_f32_16x16x32_bf16 v[88:91], v[174:177], v[194:197], v[88:91]
	v_mfma_f32_16x16x32_bf16 v[84:87], v[150:153], v[202:205], v[84:87]
	v_mfma_f32_16x16x32_bf16 v[80:83], v[174:177], v[202:205], v[80:83]
	v_mfma_f32_16x16x32_bf16 v[76:79], v[150:153], v[228:231], v[76:79]
	v_mfma_f32_16x16x32_bf16 v[72:75], v[174:177], v[228:231], v[72:75]
	v_mfma_f32_16x16x32_bf16 v[68:71], v[150:153], v[236:239], v[68:71]
	v_mfma_f32_16x16x32_bf16 v[64:67], v[174:177], v[236:239], v[64:67]
	v_mfma_f32_16x16x32_bf16 v[92:95], v[154:157], v[198:201], v[92:95]
	v_mfma_f32_16x16x32_bf16 v[88:91], v[190:193], v[198:201], v[88:91]
	v_mfma_f32_16x16x32_bf16 v[84:87], v[154:157], v[224:227], v[84:87]
	v_mfma_f32_16x16x32_bf16 v[80:83], v[190:193], v[224:227], v[80:83]
	v_mfma_f32_16x16x32_bf16 v[76:79], v[154:157], v[232:235], v[76:79]
	v_mfma_f32_16x16x32_bf16 v[72:75], v[190:193], v[232:235], v[72:75]
	v_mfma_f32_16x16x32_bf16 v[68:71], v[154:157], v[240:243], v[68:71]
	v_mfma_f32_16x16x32_bf16 v[64:67], v[190:193], v[240:243], v[64:67]
	s_setprio 0
	s_barrier
; #define PG8_STAGE(bufoff, gbase, voff) do { _Pragma("unroll") for (int _i = 0; _i < 2; ++_i) \
;         __builtin_amdgcn_global_load_lds((const unsigned*)((const char*)(gbase) + (voff)[_i]), (LAS unsigned*)(lds + (bufoff) + ldsw + _i * 8192), 16, 0, 0); } while (0)
; #define PG8_LDA(dst, b, h) do { _Pragma("unroll") for (int m = 0; m < 4; ++m) _Pragma("unroll") for (int k = 0; k < 2; ++k) dst[m][k] = *(const LAS bf16x8*)(lds + PG8_SA(b, h) + aoff + m * 2048 + k * 1024); } while (0)
; #define PG8_MMA(ai, bj, At, Bt) do { __builtin_amdgcn_s_setprio(1); _Pragma("unroll") for (int m = 0; m < 4; ++m) _Pragma("unroll") for (int n = 0; n < 2; ++n) _Pragma("unroll") for (int k = 0; k < 2; ++k) \
;         acc[ai][bj][m][n] = __builtin_amdgcn_mfma_f32_16x16x32_bf16(Bt[n][k], At[m][k], acc[ai][bj][m][n], 0, 0, 0); __builtin_amdgcn_s_setprio(0); } while (0)
; #define PG8_WAIT_V(n) asm volatile("s_waitcnt vmcnt(" #n ")" ::: "memory")
; #define PG8_WAIT_L(n) asm volatile("s_waitcnt lgkmcnt(" #n ")" ::: "memory")
; #define PG8_BAR __builtin_amdgcn_s_barrier()
; #define PG8_SCHED __builtin_amdgcn_sched_barrier(0)
;     ...
;             PG8_WAIT_V(8); PG8_WAIT_L(0); PG8_BAR; PG8_MMA(0, 0, At, B0); PG8_MMA(0, 1, At, B1); PG8_BAR; PG8_SCHED;
;             PG8_LDA(At, 1, 1); PG8_STAGE(PG8_SB(1, 0), b3, voffB); PG8_STAGE(PG8_SB(1, 1), b3 + hstepB, voffB); PG8_STAGE(PG8_SA(1, 0), a3, voffA);
;             PG8_WAIT_V(8); PG8_WAIT_L(0); PG8_BAR; PG8_MMA(1, 0, At, B0); PG8_MMA(1, 1, At, B1); PG8_BAR; PG8_SCHED;
;         }
;         if (wr == 0) PG8_BAR;
	s_add_i32 s19, s19, s10
	v_lshl_add_u64 v[178:179], v[178:179], 0, s[70:71]
	s_mov_b32 m0, s19
	ds_read_b128 v[194:197], v188 offset:49152
	ds_read_b128 v[198:201], v188 offset:50176
	ds_read_b128 v[202:205], v188 offset:51200
	ds_read_b128 v[224:227], v188 offset:52224
	ds_read_b128 v[228:231], v188 offset:53248
	ds_read_b128 v[232:235], v188 offset:54272
	ds_read_b128 v[236:239], v188 offset:55296
	ds_read_b128 v[240:243], v188 offset:56320
	global_load_lds_dwordx4 v[178:179], off
	v_lshl_add_u64 v[178:179], v[212:213], 0, s[70:71]
	s_add_i32 m0, s19, 0x2000
	s_add_i32 s19, s27, s10
	global_load_lds_dwordx4 v[178:179], off
	v_lshl_add_u64 v[178:179], v[218:219], 0, s[70:71]
	s_mov_b32 m0, s19
	v_lshl_add_u64 v[158:159], v[158:159], 0, s[70:71]
	global_load_lds_dwordx4 v[178:179], off
	s_add_i32 m0, s19, 0x2000
	s_nop 0
	global_load_lds_dwordx4 v[158:159], off
	v_lshl_add_u64 v[158:159], v[244:245], 0, s[70:71]
	s_mov_b32 m0, s62
	s_nop 0
	global_load_lds_dwordx4 v[158:159], off
	v_lshl_add_u64 v[158:159], v[246:247], 0, s[70:71]
	s_mov_b32 m0, s63
	s_nop 0
	global_load_lds_dwordx4 v[158:159], off
	s_waitcnt vmcnt(8)
	s_waitcnt lgkmcnt(0)
	s_barrier
	s_setprio 1
	s_waitcnt lgkmcnt(0)
	v_mfma_f32_16x16x32_bf16 v[60:63], v[134:137], v[194:197], v[60:63]
	v_mfma_f32_16x16x32_bf16 v[56:59], v[142:145], v[194:197], v[56:59]
	v_mfma_f32_16x16x32_bf16 v[52:55], v[134:137], v[202:205], v[52:55]
	v_mfma_f32_16x16x32_bf16 v[48:51], v[142:145], v[202:205], v[48:51]
	v_mfma_f32_16x16x32_bf16 v[44:47], v[134:137], v[228:231], v[44:47]
	v_mfma_f32_16x16x32_bf16 v[40:43], v[142:145], v[228:231], v[40:43]
	v_mfma_f32_16x16x32_bf16 v[36:39], v[134:137], v[236:239], v[36:39]
	v_mfma_f32_16x16x32_bf16 v[32:35], v[142:145], v[236:239], v[32:35]
	v_mfma_f32_16x16x32_bf16 v[60:63], v[138:141], v[198:201], v[60:63]
	v_mfma_f32_16x16x32_bf16 v[56:59], v[146:149], v[198:201], v[56:59]
	v_mfma_f32_16x16x32_bf16 v[52:55], v[138:141], v[224:227], v[52:55]
	v_mfma_f32_16x16x32_bf16 v[48:51], v[146:149], v[224:227], v[48:51]
	v_mfma_f32_16x16x32_bf16 v[44:47], v[138:141], v[232:235], v[44:47]
	v_mfma_f32_16x16x32_bf16 v[40:43], v[146:149], v[232:235], v[40:43]
	v_mfma_f32_16x16x32_bf16 v[36:39], v[138:141], v[240:243], v[36:39]
	v_mfma_f32_16x16x32_bf16 v[32:35], v[146:149], v[240:243], v[32:35]
	s_setprio 0
	s_setprio 1
	v_mfma_f32_16x16x32_bf16 v[28:31], v[150:153], v[194:197], v[28:31]
	v_mfma_f32_16x16x32_bf16 v[24:27], v[174:177], v[194:197], v[24:27]
	v_mfma_f32_16x16x32_bf16 v[20:23], v[150:153], v[202:205], v[20:23]
	v_mfma_f32_16x16x32_bf16 v[16:19], v[174:177], v[202:205], v[16:19]
	v_mfma_f32_16x16x32_bf16 v[12:15], v[150:153], v[228:231], v[12:15]
	v_mfma_f32_16x16x32_bf16 v[8:11], v[174:177], v[228:231], v[8:11]
	v_mfma_f32_16x16x32_bf16 v[4:7], v[150:153], v[236:239], v[4:7]
	v_mfma_f32_16x16x32_bf16 v[0:3], v[174:177], v[236:239], v[0:3]
	v_mfma_f32_16x16x32_bf16 v[28:31], v[154:157], v[198:201], v[28:31]
	v_mfma_f32_16x16x32_bf16 v[24:27], v[190:193], v[198:201], v[24:27]
	v_mfma_f32_16x16x32_bf16 v[20:23], v[154:157], v[224:227], v[20:23]
	v_mfma_f32_16x16x32_bf16 v[16:19], v[190:193], v[224:227], v[16:19]
	v_mfma_f32_16x16x32_bf16 v[12:15], v[154:157], v[232:235], v[12:15]
	v_mfma_f32_16x16x32_bf16 v[8:11], v[190:193], v[232:235], v[8:11]
	v_mfma_f32_16x16x32_bf16 v[4:7], v[154:157], v[240:243], v[4:7]
	v_mfma_f32_16x16x32_bf16 v[0:3], v[190:193], v[240:243], v[0:3]
	s_setprio 0
	s_barrier
	s_add_u32 s0, s0, 0x100
	s_addc_u32 s1, s1, 0
	v_lshl_add_u64 v[130:131], v[130:131], 0, s[94:95]
	v_lshl_add_u64 v[128:129], v[128:129], 0, s[94:95]
	s_cmp_ge_u32 s57, s16
	s_mov_b32 s38, s57
	s_cbranch_scc0 .LBB0_318
	v_readlane_b32 s0, v254, 50
	v_readlane_b32 s1, v254, 51
	s_and_b64 vcc, exec, s[0:1]
	s_mov_b32 s68, 0x134000
	s_mov_b32 s69, 0x160000
	s_cbranch_vccz .LBB0_321
	s_barrier
